# phase-1 non-V output stores as full 128-B lines (8 rows x 128 B per dwordx4; permlane16 swap + DPP half-row exchange)
# baseline (speedup 1.0000x reference)
; DI unsigned pack2(float lo, float hi) { f2_t v = {lo, hi}; h2_t b = __builtin_convertvector(v, h2_t); return __builtin_bit_cast(unsigned, b); }
; DI float sigmoidf_(float x) { return 1.0f / (1.0f + __expf(-x)); }
; DI void phase_proj(const Params& P, int l, char* smem) {
;     ...
;       for (int mt = 0; mt < 4; ++mt) {
;         const int row = row0 + mt * 16 + lr;
; #pragma unroll
;         for (int nt = 0; nt < 4; ++nt) {
;           f32x4 v = acc[mt][nt] * sc;
;           if (sig) { v[0] = sigmoidf_(v[0]); v[1] = sigmoidf_(v[1]); v[2] = sigmoidf_(v[2]); v[3] = sigmoidf_(v[3]); }
;           *(uint2*)(Pb + (size_t)row * PW + col0 + nt * 16 + 4 * g) = make_uint2(pack2(v[0], v[1]), pack2(v[2], v[3]));
;         }
;       }
.LBB0_662:
	s_or_b64 exec, exec, s[4:5]
	v_cvt_pk_f16_f32 v24, v24, v25
	v_cvt_pk_f16_f32 v25, v26, v27
	v_mov_b32_e32 v222, v24
	v_mov_b32_e32 v223, v25
	s_nop 1
	v_permlane16_swap_b32_e32 v220, v222
	v_permlane16_swap_b32_e32 v221, v223
	v_pk_mul_f32 v[24:25], v[32:33], v[120:121]
	v_pk_mul_f32 v[26:27], v[72:73], v[118:119]
	s_and_saveexec_b64 s[4:5], s[20:21]
	s_cbranch_execz .LBB0_664
	v_mul_f32_e32 v24, 0xbfb8aa3b, v24
	v_mul_f32_e32 v25, 0xbfb8aa3b, v25
	v_exp_f32_e32 v24, v24
	v_exp_f32_e32 v25, v25
	v_mul_f32_e32 v26, 0xbfb8aa3b, v26
	v_mul_f32_e32 v27, 0xbfb8aa3b, v27
	v_exp_f32_e32 v26, v26
	v_pk_add_f32 v[24:25], v[24:25], 1.0 op_sel_hi:[1,0]
	v_exp_f32_e32 v27, v27
	v_div_scale_f32 v32, s[22:23], v25, v25, 1.0
	v_rcp_f32_e32 v33, v32
	v_pk_add_f32 v[26:27], v[26:27], 1.0 op_sel_hi:[1,0]
	v_fma_f32 v34, -v32, v33, 1.0
	v_fmac_f32_e32 v33, v34, v33
	v_div_scale_f32 v34, vcc, 1.0, v25, 1.0
	v_mul_f32_e32 v35, v34, v33
	v_fma_f32 v36, -v32, v35, v34
	v_fmac_f32_e32 v35, v36, v33
	v_fma_f32 v32, -v32, v35, v34
	v_div_fmas_f32 v32, v32, v33, v35
	v_div_fixup_f32 v25, v32, v25, 1.0
	v_div_scale_f32 v32, s[22:23], v24, v24, 1.0
	v_rcp_f32_e32 v33, v32
	s_nop 0
	v_fma_f32 v34, -v32, v33, 1.0
	v_fmac_f32_e32 v33, v34, v33
	v_div_scale_f32 v34, vcc, 1.0, v24, 1.0
	v_mul_f32_e32 v35, v34, v33
	v_fma_f32 v36, -v32, v35, v34
	v_fmac_f32_e32 v35, v36, v33
	v_fma_f32 v32, -v32, v35, v34
	v_div_fmas_f32 v32, v32, v33, v35
	v_div_fixup_f32 v24, v32, v24, 1.0
	v_div_scale_f32 v32, s[22:23], v27, v27, 1.0
	v_rcp_f32_e32 v33, v32
	s_nop 0
	v_fma_f32 v34, -v32, v33, 1.0
	v_fmac_f32_e32 v33, v34, v33
	v_div_scale_f32 v34, vcc, 1.0, v27, 1.0
	v_mul_f32_e32 v35, v34, v33
	v_fma_f32 v36, -v32, v35, v34
	v_fmac_f32_e32 v35, v36, v33
	v_fma_f32 v32, -v32, v35, v34
	v_div_fmas_f32 v32, v32, v33, v35
	v_div_fixup_f32 v27, v32, v27, 1.0
	v_div_scale_f32 v32, s[22:23], v26, v26, 1.0
	v_rcp_f32_e32 v33, v32
	s_nop 0
	v_fma_f32 v34, -v32, v33, 1.0
	v_fmac_f32_e32 v33, v34, v33
	v_div_scale_f32 v34, vcc, 1.0, v26, 1.0
	v_mul_f32_e32 v35, v34, v33
	v_fma_f32 v36, -v32, v35, v34
	v_fmac_f32_e32 v35, v36, v33
	v_fma_f32 v32, -v32, v35, v34
	v_div_fmas_f32 v32, v32, v33, v35
	v_div_fixup_f32 v26, v32, v26, 1.0

; DI unsigned pack2(float lo, float hi) { f2_t v = {lo, hi}; h2_t b = __builtin_convertvector(v, h2_t); return __builtin_bit_cast(unsigned, b); }
; DI float sigmoidf_(float x) { return 1.0f / (1.0f + __expf(-x)); }
; DI void phase_proj(const Params& P, int l, char* smem) {
;     ...
;       for (int mt = 0; mt < 4; ++mt) {
;         const int row = row0 + mt * 16 + lr;
; #pragma unroll
;         for (int nt = 0; nt < 4; ++nt) {
;           f32x4 v = acc[mt][nt] * sc;
;           if (sig) { v[0] = sigmoidf_(v[0]); v[1] = sigmoidf_(v[1]); v[2] = sigmoidf_(v[2]); v[3] = sigmoidf_(v[3]); }
;           *(uint2*)(Pb + (size_t)row * PW + col0 + nt * 16 + 4 * g) = make_uint2(pack2(v[0], v[1]), pack2(v[2], v[3]));
;         }
;       }
.LBB0_666:
	s_or_b64 exec, exec, s[4:5]
	v_cvt_pk_f16_f32 v32, v32, v33
	v_cvt_pk_f16_f32 v33, v26, v27
	v_pk_mul_f32 v[22:23], v[24:25], v[22:23]
	v_pk_mul_f32 v[24:25], v[72:73], v[20:21]
	v_mov_b32_e32 v226, v32
	v_mov_b32_e32 v227, v33
	v_and_b32_e32 v232, 16, v148
	v_lshrrev_b32_e32 v233, 1, v232
	v_add_u32_e32 v232, v232, v233
	v_and_b32_e32 v233, 8, v148
	v_mul_u32_u24_e32 v233, 0x32f8, v233
	v_sub_u32_e32 v232, v232, v233
	v_ashrrev_i32_e32 v233, 31, v232
	v_lshl_add_u64 v[232:233], v[232:233], 0, v[30:31]
	v_mov_b32_e32 v236, 0x19800
	v_mov_b32_e32 v237, 0
	v_lshl_add_u64 v[234:235], v[236:237], 0, v[232:233]
	v_permlane16_swap_b32_e32 v224, v226
	v_permlane16_swap_b32_e32 v225, v227
	s_nop 1
	v_mov_b32_dpp v228, v220 row_ror:8 row_mask:0xf bank_mask:0x3
	v_mov_b32_dpp v229, v221 row_ror:8 row_mask:0xf bank_mask:0x3
	v_mov_b32_dpp v230, v222 row_ror:8 row_mask:0xf bank_mask:0x3
	v_mov_b32_dpp v231, v223 row_ror:8 row_mask:0xf bank_mask:0x3
	v_mov_b32_dpp v220, v224 row_ror:8 row_mask:0xf bank_mask:0xc
	v_mov_b32_dpp v221, v225 row_ror:8 row_mask:0xf bank_mask:0xc
	v_mov_b32_dpp v222, v226 row_ror:8 row_mask:0xf bank_mask:0xc
	v_mov_b32_dpp v223, v227 row_ror:8 row_mask:0xf bank_mask:0xc
	v_mov_b32_dpp v224, v228 quad_perm:[0,1,2,3] row_mask:0xf bank_mask:0x3
	v_mov_b32_dpp v225, v229 quad_perm:[0,1,2,3] row_mask:0xf bank_mask:0x3
	v_mov_b32_dpp v226, v230 quad_perm:[0,1,2,3] row_mask:0xf bank_mask:0x3
	v_mov_b32_dpp v227, v231 quad_perm:[0,1,2,3] row_mask:0xf bank_mask:0x3
	global_store_dwordx4 v[232:233], v[220:223], off
	global_store_dwordx4 v[234:235], v[224:227], off
	s_and_saveexec_b64 s[4:5], s[20:21]
	s_cbranch_execz .LBB0_668
	v_mul_f32_e32 v22, 0xbfb8aa3b, v22
	v_mul_f32_e32 v23, 0xbfb8aa3b, v23
	v_exp_f32_e32 v22, v22
	v_exp_f32_e32 v23, v23
	v_mul_f32_e32 v20, 0xbfb8aa3b, v24
	v_mul_f32_e32 v21, 0xbfb8aa3b, v25
	v_exp_f32_e32 v20, v20
	v_pk_add_f32 v[22:23], v[22:23], 1.0 op_sel_hi:[1,0]
	v_exp_f32_e32 v21, v21
	v_div_scale_f32 v24, s[22:23], v23, v23, 1.0
	v_rcp_f32_e32 v25, v24
	v_pk_add_f32 v[20:21], v[20:21], 1.0 op_sel_hi:[1,0]
	v_fma_f32 v26, -v24, v25, 1.0
	v_fmac_f32_e32 v25, v26, v25
	v_div_scale_f32 v26, vcc, 1.0, v23, 1.0
	v_mul_f32_e32 v27, v26, v25
	v_fma_f32 v30, -v24, v27, v26
	v_fmac_f32_e32 v27, v30, v25
	v_fma_f32 v24, -v24, v27, v26
	v_div_fmas_f32 v24, v24, v25, v27
	v_div_fixup_f32 v23, v24, v23, 1.0
	v_div_scale_f32 v24, s[22:23], v22, v22, 1.0
	v_rcp_f32_e32 v25, v24
	s_nop 0
	v_fma_f32 v26, -v24, v25, 1.0
	v_fmac_f32_e32 v25, v26, v25
	v_div_scale_f32 v26, vcc, 1.0, v22, 1.0
	v_mul_f32_e32 v27, v26, v25
	v_fma_f32 v30, -v24, v27, v26
	v_fmac_f32_e32 v27, v30, v25
	v_fma_f32 v24, -v24, v27, v26
	v_div_fmas_f32 v24, v24, v25, v27
	v_div_fixup_f32 v22, v24, v22, 1.0
	v_div_scale_f32 v24, s[22:23], v21, v21, 1.0
	v_rcp_f32_e32 v25, v24
	s_nop 0
	v_fma_f32 v26, -v24, v25, 1.0
	v_fmac_f32_e32 v25, v26, v25
	v_div_scale_f32 v26, vcc, 1.0, v21, 1.0
	v_mul_f32_e32 v27, v26, v25
	v_fma_f32 v30, -v24, v27, v26
	v_fmac_f32_e32 v27, v30, v25
	v_fma_f32 v24, -v24, v27, v26
	v_div_fmas_f32 v24, v24, v25, v27
	v_div_fixup_f32 v25, v24, v21, 1.0
	v_div_scale_f32 v21, s[22:23], v20, v20, 1.0
	v_rcp_f32_e32 v24, v21
	s_nop 0
	v_fma_f32 v26, -v21, v24, 1.0
	v_fmac_f32_e32 v24, v26, v24
	v_div_scale_f32 v26, vcc, 1.0, v20, 1.0
	v_mul_f32_e32 v27, v26, v24
	v_fma_f32 v30, -v21, v27, v26
	v_fmac_f32_e32 v27, v30, v24
	v_fma_f32 v21, -v21, v27, v26
	v_div_fmas_f32 v21, v21, v24, v27
	v_div_fixup_f32 v24, v21, v20, 1.0
.LBB0_668:
	s_or_b64 exec, exec, s[4:5]
	v_cvt_pk_f16_f32 v24, v24, v25
	v_cvt_pk_f16_f32 v25, v22, v23
	v_mov_b32_e32 v22, v72
	v_mov_b32_e32 v23, v72
	v_mad_i64_i32 v[20:21], s[4:5], v68, s0, v[28:29]
	v_pk_mul_f32 v[18:19], v[22:23], v[18:19]
	v_pk_mul_f32 v[16:17], v[72:73], v[16:17]
	v_mov_b32_e32 v220, v24
	v_mov_b32_e32 v221, v25
	s_and_saveexec_b64 s[4:5], s[20:21]
	s_cbranch_execz .LBB0_670
	v_mul_f32_e32 v18, 0xbfb8aa3b, v18
	v_mul_f32_e32 v19, 0xbfb8aa3b, v19
	v_exp_f32_e32 v18, v18
	v_exp_f32_e32 v19, v19
	v_mul_f32_e32 v16, 0xbfb8aa3b, v16
	v_mul_f32_e32 v17, 0xbfb8aa3b, v17
	v_exp_f32_e32 v16, v16
	v_pk_add_f32 v[18:19], v[18:19], 1.0 op_sel_hi:[1,0]
	v_exp_f32_e32 v17, v17
	v_div_scale_f32 v24, s[22:23], v19, v19, 1.0
	v_rcp_f32_e32 v25, v24
	v_pk_add_f32 v[16:17], v[16:17], 1.0 op_sel_hi:[1,0]
	v_fma_f32 v26, -v24, v25, 1.0
	v_fmac_f32_e32 v25, v26, v25
	v_div_scale_f32 v26, vcc, 1.0, v19, 1.0
	v_mul_f32_e32 v27, v26, v25
	v_fma_f32 v30, -v24, v27, v26
	v_fmac_f32_e32 v27, v30, v25
	v_fma_f32 v24, -v24, v27, v26
	v_div_fmas_f32 v24, v24, v25, v27
	v_div_fixup_f32 v19, v24, v19, 1.0
	v_div_scale_f32 v24, s[22:23], v18, v18, 1.0
	v_rcp_f32_e32 v25, v24
	s_nop 0
	v_fma_f32 v26, -v24, v25, 1.0
	v_fmac_f32_e32 v25, v26, v25
	v_div_scale_f32 v26, vcc, 1.0, v18, 1.0
	v_mul_f32_e32 v27, v26, v25
	v_fma_f32 v30, -v24, v27, v26
	v_fmac_f32_e32 v27, v30, v25
	v_fma_f32 v24, -v24, v27, v26
	v_div_fmas_f32 v24, v24, v25, v27
	v_div_fixup_f32 v18, v24, v18, 1.0
	v_div_scale_f32 v24, s[22:23], v17, v17, 1.0
	v_rcp_f32_e32 v25, v24
	s_nop 0
	v_fma_f32 v26, -v24, v25, 1.0
	v_fmac_f32_e32 v25, v26, v25
	v_div_scale_f32 v26, vcc, 1.0, v17, 1.0
	v_mul_f32_e32 v27, v26, v25
	v_fma_f32 v30, -v24, v27, v26
	v_fmac_f32_e32 v27, v30, v25
	v_fma_f32 v24, -v24, v27, v26
	v_div_fmas_f32 v24, v24, v25, v27
	v_div_fixup_f32 v17, v24, v17, 1.0
	v_div_scale_f32 v24, s[22:23], v16, v16, 1.0
	v_rcp_f32_e32 v25, v24
	s_nop 0
	v_fma_f32 v26, -v24, v25, 1.0
	v_fmac_f32_e32 v25, v26, v25
	v_div_scale_f32 v26, vcc, 1.0, v16, 1.0
	v_mul_f32_e32 v27, v26, v25
	v_fma_f32 v30, -v24, v27, v26
	v_fmac_f32_e32 v27, v30, v25
	v_fma_f32 v24, -v24, v27, v26
	v_div_fmas_f32 v24, v24, v25, v27
	v_div_fixup_f32 v16, v24, v16, 1.0
; DI unsigned pack2(float lo, float hi) { f2_t v = {lo, hi}; h2_t b = __builtin_convertvector(v, h2_t); return __builtin_bit_cast(unsigned, b); }
; DI float sigmoidf_(float x) { return 1.0f / (1.0f + __expf(-x)); }
; DI void phase_proj(const Params& P, int l, char* smem) {
;     ...
;       for (int mt = 0; mt < 4; ++mt) {
;         const int row = row0 + mt * 16 + lr;
; #pragma unroll
;         for (int nt = 0; nt < 4; ++nt) {
;           f32x4 v = acc[mt][nt] * sc;
;           if (sig) { v[0] = sigmoidf_(v[0]); v[1] = sigmoidf_(v[1]); v[2] = sigmoidf_(v[2]); v[3] = sigmoidf_(v[3]); }
;           *(uint2*)(Pb + (size_t)row * PW + col0 + nt * 16 + 4 * g) = make_uint2(pack2(v[0], v[1]), pack2(v[2], v[3]));
;         }
;       }
.LBB0_670:
	s_or_b64 exec, exec, s[4:5]
	v_cvt_pk_f16_f32 v16, v16, v17
	v_cvt_pk_f16_f32 v17, v18, v19
	v_mov_b32_e32 v222, v16
	v_mov_b32_e32 v223, v17
	s_nop 1
	v_permlane16_swap_b32_e32 v220, v222
	v_permlane16_swap_b32_e32 v221, v223
	v_pk_mul_f32 v[16:17], v[22:23], v[112:113]
	v_pk_mul_f32 v[18:19], v[72:73], v[110:111]
	s_and_saveexec_b64 s[4:5], s[20:21]
	s_cbranch_execz .LBB0_672
	v_mul_f32_e32 v16, 0xbfb8aa3b, v16
	v_mul_f32_e32 v17, 0xbfb8aa3b, v17
	v_exp_f32_e32 v16, v16
	v_exp_f32_e32 v17, v17
	v_mul_f32_e32 v18, 0xbfb8aa3b, v18
	v_mul_f32_e32 v19, 0xbfb8aa3b, v19
	v_exp_f32_e32 v18, v18
	v_pk_add_f32 v[16:17], v[16:17], 1.0 op_sel_hi:[1,0]
	v_exp_f32_e32 v19, v19
	v_div_scale_f32 v22, s[22:23], v17, v17, 1.0
	v_rcp_f32_e32 v23, v22
	v_pk_add_f32 v[18:19], v[18:19], 1.0 op_sel_hi:[1,0]
	v_fma_f32 v24, -v22, v23, 1.0
	v_fmac_f32_e32 v23, v24, v23
	v_div_scale_f32 v24, vcc, 1.0, v17, 1.0
	v_mul_f32_e32 v25, v24, v23
	v_fma_f32 v26, -v22, v25, v24
	v_fmac_f32_e32 v25, v26, v23
	v_fma_f32 v22, -v22, v25, v24
	v_div_fmas_f32 v22, v22, v23, v25
	v_div_fixup_f32 v17, v22, v17, 1.0
	v_div_scale_f32 v22, s[22:23], v16, v16, 1.0
	v_rcp_f32_e32 v23, v22
	s_nop 0
	v_fma_f32 v24, -v22, v23, 1.0
	v_fmac_f32_e32 v23, v24, v23
	v_div_scale_f32 v24, vcc, 1.0, v16, 1.0
	v_mul_f32_e32 v25, v24, v23
	v_fma_f32 v26, -v22, v25, v24
	v_fmac_f32_e32 v25, v26, v23
	v_fma_f32 v22, -v22, v25, v24
	v_div_fmas_f32 v22, v22, v23, v25
	v_div_fixup_f32 v16, v22, v16, 1.0
	v_div_scale_f32 v22, s[22:23], v19, v19, 1.0
	v_rcp_f32_e32 v23, v22
	s_nop 0
	v_fma_f32 v24, -v22, v23, 1.0
	v_fmac_f32_e32 v23, v24, v23
	v_div_scale_f32 v24, vcc, 1.0, v19, 1.0
	v_mul_f32_e32 v25, v24, v23
	v_fma_f32 v26, -v22, v25, v24
	v_fmac_f32_e32 v25, v26, v23
	v_fma_f32 v22, -v22, v25, v24
	v_div_fmas_f32 v22, v22, v23, v25
	v_div_fixup_f32 v19, v22, v19, 1.0
	v_div_scale_f32 v22, s[22:23], v18, v18, 1.0
	v_rcp_f32_e32 v23, v22
	s_nop 0
	v_fma_f32 v24, -v22, v23, 1.0
	v_fmac_f32_e32 v23, v24, v23
	v_div_scale_f32 v24, vcc, 1.0, v18, 1.0
	v_mul_f32_e32 v25, v24, v23
	v_fma_f32 v26, -v22, v25, v24
	v_fmac_f32_e32 v25, v26, v23
	v_fma_f32 v22, -v22, v25, v24
	v_div_fmas_f32 v22, v22, v23, v25
	v_div_fixup_f32 v18, v22, v18, 1.0
.LBB0_672:
	s_or_b64 exec, exec, s[4:5]
	v_cvt_pk_f16_f32 v18, v18, v19
	v_cvt_pk_f16_f32 v19, v16, v17
	v_mov_b32_e32 v16, v72
	v_mov_b32_e32 v17, v72
	v_mov_b32_e32 v224, v18
	v_mov_b32_e32 v225, v19
	v_pk_mul_f32 v[18:19], v[16:17], v[108:109]
	v_pk_mul_f32 v[22:23], v[72:73], v[106:107]
	s_and_saveexec_b64 s[4:5], s[20:21]
	s_cbranch_execz .LBB0_674
	v_mul_f32_e32 v18, 0xbfb8aa3b, v18
	v_mul_f32_e32 v19, 0xbfb8aa3b, v19
	v_exp_f32_e32 v18, v18
	v_exp_f32_e32 v19, v19
	v_mul_f32_e32 v22, 0xbfb8aa3b, v22
	v_mul_f32_e32 v23, 0xbfb8aa3b, v23
	v_exp_f32_e32 v22, v22
	v_pk_add_f32 v[18:19], v[18:19], 1.0 op_sel_hi:[1,0]
	v_exp_f32_e32 v23, v23
	v_div_scale_f32 v24, s[22:23], v19, v19, 1.0
	v_rcp_f32_e32 v25, v24
	v_pk_add_f32 v[22:23], v[22:23], 1.0 op_sel_hi:[1,0]
	v_fma_f32 v26, -v24, v25, 1.0
	v_fmac_f32_e32 v25, v26, v25
	v_div_scale_f32 v26, vcc, 1.0, v19, 1.0
	v_mul_f32_e32 v27, v26, v25
	v_fma_f32 v30, -v24, v27, v26
	v_fmac_f32_e32 v27, v30, v25
	v_fma_f32 v24, -v24, v27, v26
	v_div_fmas_f32 v24, v24, v25, v27
	v_div_fixup_f32 v19, v24, v19, 1.0
	v_div_scale_f32 v24, s[22:23], v18, v18, 1.0
	v_rcp_f32_e32 v25, v24
	s_nop 0
	v_fma_f32 v26, -v24, v25, 1.0
	v_fmac_f32_e32 v25, v26, v25
	v_div_scale_f32 v26, vcc, 1.0, v18, 1.0
	v_mul_f32_e32 v27, v26, v25
	v_fma_f32 v30, -v24, v27, v26
	v_fmac_f32_e32 v27, v30, v25
	v_fma_f32 v24, -v24, v27, v26
	v_div_fmas_f32 v24, v24, v25, v27
	v_div_fixup_f32 v18, v24, v18, 1.0
	v_div_scale_f32 v24, s[22:23], v23, v23, 1.0
	v_rcp_f32_e32 v25, v24
	s_nop 0
	v_fma_f32 v26, -v24, v25, 1.0
	v_fmac_f32_e32 v25, v26, v25
	v_div_scale_f32 v26, vcc, 1.0, v23, 1.0
	v_mul_f32_e32 v27, v26, v25
	v_fma_f32 v30, -v24, v27, v26
	v_fmac_f32_e32 v27, v30, v25
	v_fma_f32 v24, -v24, v27, v26
	v_div_fmas_f32 v24, v24, v25, v27
	v_div_fixup_f32 v23, v24, v23, 1.0
	v_div_scale_f32 v24, s[22:23], v22, v22, 1.0
	v_rcp_f32_e32 v25, v24
	s_nop 0
	v_fma_f32 v26, -v24, v25, 1.0
	v_fmac_f32_e32 v25, v26, v25
	v_div_scale_f32 v26, vcc, 1.0, v22, 1.0
	v_mul_f32_e32 v27, v26, v25
	v_fma_f32 v30, -v24, v27, v26
	v_fmac_f32_e32 v27, v30, v25
	v_fma_f32 v24, -v24, v27, v26
	v_div_fmas_f32 v24, v24, v25, v27
	v_div_fixup_f32 v22, v24, v22, 1.0
; DI unsigned pack2(float lo, float hi) { f2_t v = {lo, hi}; h2_t b = __builtin_convertvector(v, h2_t); return __builtin_bit_cast(unsigned, b); }
; DI float sigmoidf_(float x) { return 1.0f / (1.0f + __expf(-x)); }
; DI void phase_proj(const Params& P, int l, char* smem) {
;     ...
;       for (int mt = 0; mt < 4; ++mt) {
;         const int row = row0 + mt * 16 + lr;
; #pragma unroll
;         for (int nt = 0; nt < 4; ++nt) {
;           f32x4 v = acc[mt][nt] * sc;
;           if (sig) { v[0] = sigmoidf_(v[0]); v[1] = sigmoidf_(v[1]); v[2] = sigmoidf_(v[2]); v[3] = sigmoidf_(v[3]); }
;           *(uint2*)(Pb + (size_t)row * PW + col0 + nt * 16 + 4 * g) = make_uint2(pack2(v[0], v[1]), pack2(v[2], v[3]));
;         }
;       }
.LBB0_674:
	s_or_b64 exec, exec, s[4:5]
	v_cvt_pk_f16_f32 v22, v22, v23
	v_cvt_pk_f16_f32 v23, v18, v19
	v_pk_mul_f32 v[14:15], v[16:17], v[14:15]
	v_pk_mul_f32 v[16:17], v[72:73], v[12:13]
	v_mov_b32_e32 v226, v22
	v_mov_b32_e32 v227, v23
	v_and_b32_e32 v232, 16, v148
	v_lshrrev_b32_e32 v233, 1, v232
	v_add_u32_e32 v232, v232, v233
	v_and_b32_e32 v233, 8, v148
	v_mul_u32_u24_e32 v233, 0x32f8, v233
	v_sub_u32_e32 v232, v232, v233
	v_ashrrev_i32_e32 v233, 31, v232
	v_lshl_add_u64 v[232:233], v[232:233], 0, v[20:21]
	v_mov_b32_e32 v236, 0x19800
	v_mov_b32_e32 v237, 0
	v_lshl_add_u64 v[234:235], v[236:237], 0, v[232:233]
	v_permlane16_swap_b32_e32 v224, v226
	v_permlane16_swap_b32_e32 v225, v227
	s_nop 1
	v_mov_b32_dpp v228, v220 row_ror:8 row_mask:0xf bank_mask:0x3
	v_mov_b32_dpp v229, v221 row_ror:8 row_mask:0xf bank_mask:0x3
	v_mov_b32_dpp v230, v222 row_ror:8 row_mask:0xf bank_mask:0x3
	v_mov_b32_dpp v231, v223 row_ror:8 row_mask:0xf bank_mask:0x3
	v_mov_b32_dpp v220, v224 row_ror:8 row_mask:0xf bank_mask:0xc
	v_mov_b32_dpp v221, v225 row_ror:8 row_mask:0xf bank_mask:0xc
	v_mov_b32_dpp v222, v226 row_ror:8 row_mask:0xf bank_mask:0xc
	v_mov_b32_dpp v223, v227 row_ror:8 row_mask:0xf bank_mask:0xc
	v_mov_b32_dpp v224, v228 quad_perm:[0,1,2,3] row_mask:0xf bank_mask:0x3
	v_mov_b32_dpp v225, v229 quad_perm:[0,1,2,3] row_mask:0xf bank_mask:0x3
	v_mov_b32_dpp v226, v230 quad_perm:[0,1,2,3] row_mask:0xf bank_mask:0x3
	v_mov_b32_dpp v227, v231 quad_perm:[0,1,2,3] row_mask:0xf bank_mask:0x3
	global_store_dwordx4 v[232:233], v[220:223], off
	global_store_dwordx4 v[234:235], v[224:227], off
	s_and_saveexec_b64 s[4:5], s[20:21]
	s_cbranch_execz .LBB0_676
	v_mul_f32_e32 v14, 0xbfb8aa3b, v14
	v_mul_f32_e32 v15, 0xbfb8aa3b, v15
	v_exp_f32_e32 v14, v14
	v_exp_f32_e32 v15, v15
	v_mul_f32_e32 v12, 0xbfb8aa3b, v16
	v_mul_f32_e32 v13, 0xbfb8aa3b, v17
	v_exp_f32_e32 v12, v12
	v_pk_add_f32 v[14:15], v[14:15], 1.0 op_sel_hi:[1,0]
	v_exp_f32_e32 v13, v13
	v_div_scale_f32 v16, s[22:23], v15, v15, 1.0
	v_rcp_f32_e32 v17, v16
	v_pk_add_f32 v[12:13], v[12:13], 1.0 op_sel_hi:[1,0]
	v_fma_f32 v18, -v16, v17, 1.0
	v_fmac_f32_e32 v17, v18, v17
	v_div_scale_f32 v18, vcc, 1.0, v15, 1.0
	v_mul_f32_e32 v19, v18, v17
	v_fma_f32 v20, -v16, v19, v18
	v_fmac_f32_e32 v19, v20, v17
	v_fma_f32 v16, -v16, v19, v18
	v_div_fmas_f32 v16, v16, v17, v19
	v_div_fixup_f32 v15, v16, v15, 1.0
	v_div_scale_f32 v16, s[22:23], v14, v14, 1.0
	v_rcp_f32_e32 v17, v16
	s_nop 0
	v_fma_f32 v18, -v16, v17, 1.0
	v_fmac_f32_e32 v17, v18, v17
	v_div_scale_f32 v18, vcc, 1.0, v14, 1.0
	v_mul_f32_e32 v19, v18, v17
	v_fma_f32 v20, -v16, v19, v18
	v_fmac_f32_e32 v19, v20, v17
	v_fma_f32 v16, -v16, v19, v18
	v_div_fmas_f32 v16, v16, v17, v19
	v_div_fixup_f32 v14, v16, v14, 1.0
	v_div_scale_f32 v16, s[22:23], v13, v13, 1.0
	v_rcp_f32_e32 v17, v16
	s_nop 0
	v_fma_f32 v18, -v16, v17, 1.0
	v_fmac_f32_e32 v17, v18, v17
	v_div_scale_f32 v18, vcc, 1.0, v13, 1.0
	v_mul_f32_e32 v19, v18, v17
	v_fma_f32 v20, -v16, v19, v18
	v_fmac_f32_e32 v19, v20, v17
	v_fma_f32 v16, -v16, v19, v18
	v_div_fmas_f32 v16, v16, v17, v19
	v_div_fixup_f32 v17, v16, v13, 1.0
	v_div_scale_f32 v13, s[22:23], v12, v12, 1.0
	v_rcp_f32_e32 v16, v13
	s_nop 0
	v_fma_f32 v18, -v13, v16, 1.0
	v_fmac_f32_e32 v16, v18, v16
	v_div_scale_f32 v18, vcc, 1.0, v12, 1.0
	v_mul_f32_e32 v19, v18, v16
	v_fma_f32 v20, -v13, v19, v18
	v_fmac_f32_e32 v19, v20, v16
	v_fma_f32 v13, -v13, v19, v18
	v_div_fmas_f32 v13, v13, v16, v19
	v_div_fixup_f32 v16, v13, v12, 1.0

; DI unsigned pack2(float lo, float hi) { f2_t v = {lo, hi}; h2_t b = __builtin_convertvector(v, h2_t); return __builtin_bit_cast(unsigned, b); }
; DI float sigmoidf_(float x) { return 1.0f / (1.0f + __expf(-x)); }
; DI void phase_proj(const Params& P, int l, char* smem) {
;     ...
;       for (int mt = 0; mt < 4; ++mt) {
;         const int row = row0 + mt * 16 + lr;
; #pragma unroll
;         for (int nt = 0; nt < 4; ++nt) {
;           f32x4 v = acc[mt][nt] * sc;
;           if (sig) { v[0] = sigmoidf_(v[0]); v[1] = sigmoidf_(v[1]); v[2] = sigmoidf_(v[2]); v[3] = sigmoidf_(v[3]); }
;           *(uint2*)(Pb + (size_t)row * PW + col0 + nt * 16 + 4 * g) = make_uint2(pack2(v[0], v[1]), pack2(v[2], v[3]));
;         }
;       }
.LBB0_678:
	s_or_b64 exec, exec, s[4:5]
	v_cvt_pk_f16_f32 v8, v8, v9
	v_cvt_pk_f16_f32 v9, v10, v11
	v_mov_b32_e32 v222, v8
	v_mov_b32_e32 v223, v9
	s_nop 1
	v_permlane16_swap_b32_e32 v220, v222
	v_permlane16_swap_b32_e32 v221, v223
	v_pk_mul_f32 v[8:9], v[14:15], v[104:105]
	v_pk_mul_f32 v[10:11], v[72:73], v[82:83]
	s_and_saveexec_b64 s[4:5], s[20:21]
	s_cbranch_execz .LBB0_680
	v_mul_f32_e32 v8, 0xbfb8aa3b, v8
	v_mul_f32_e32 v9, 0xbfb8aa3b, v9
	v_exp_f32_e32 v8, v8
	v_exp_f32_e32 v9, v9
	v_mul_f32_e32 v10, 0xbfb8aa3b, v10
	v_mul_f32_e32 v11, 0xbfb8aa3b, v11
	v_exp_f32_e32 v10, v10
	v_pk_add_f32 v[8:9], v[8:9], 1.0 op_sel_hi:[1,0]
	v_exp_f32_e32 v11, v11
	v_div_scale_f32 v14, s[22:23], v9, v9, 1.0
	v_rcp_f32_e32 v15, v14
	v_pk_add_f32 v[10:11], v[10:11], 1.0 op_sel_hi:[1,0]
	v_fma_f32 v16, -v14, v15, 1.0
	v_fmac_f32_e32 v15, v16, v15
	v_div_scale_f32 v16, vcc, 1.0, v9, 1.0
	v_mul_f32_e32 v17, v16, v15
	v_fma_f32 v18, -v14, v17, v16
	v_fmac_f32_e32 v17, v18, v15
	v_fma_f32 v14, -v14, v17, v16
	v_div_fmas_f32 v14, v14, v15, v17
	v_div_fixup_f32 v9, v14, v9, 1.0
	v_div_scale_f32 v14, s[22:23], v8, v8, 1.0
	v_rcp_f32_e32 v15, v14
	s_nop 0
	v_fma_f32 v16, -v14, v15, 1.0
	v_fmac_f32_e32 v15, v16, v15
	v_div_scale_f32 v16, vcc, 1.0, v8, 1.0
	v_mul_f32_e32 v17, v16, v15
	v_fma_f32 v18, -v14, v17, v16
	v_fmac_f32_e32 v17, v18, v15
	v_fma_f32 v14, -v14, v17, v16
	v_div_fmas_f32 v14, v14, v15, v17
	v_div_fixup_f32 v8, v14, v8, 1.0
	v_div_scale_f32 v14, s[22:23], v11, v11, 1.0
	v_rcp_f32_e32 v15, v14
	s_nop 0
	v_fma_f32 v16, -v14, v15, 1.0
	v_fmac_f32_e32 v15, v16, v15
	v_div_scale_f32 v16, vcc, 1.0, v11, 1.0
	v_mul_f32_e32 v17, v16, v15
	v_fma_f32 v18, -v14, v17, v16
	v_fmac_f32_e32 v17, v18, v15
	v_fma_f32 v14, -v14, v17, v16
	v_div_fmas_f32 v14, v14, v15, v17
	v_div_fixup_f32 v11, v14, v11, 1.0
	v_div_scale_f32 v14, s[22:23], v10, v10, 1.0
	v_rcp_f32_e32 v15, v14
	s_nop 0
	v_fma_f32 v16, -v14, v15, 1.0
	v_fmac_f32_e32 v15, v16, v15
	v_div_scale_f32 v16, vcc, 1.0, v10, 1.0
	v_mul_f32_e32 v17, v16, v15
	v_fma_f32 v18, -v14, v17, v16
	v_fmac_f32_e32 v17, v18, v15
	v_fma_f32 v14, -v14, v17, v16
	v_div_fmas_f32 v14, v14, v15, v17
	v_div_fixup_f32 v10, v14, v10, 1.0

; DI unsigned pack2(float lo, float hi) { f2_t v = {lo, hi}; h2_t b = __builtin_convertvector(v, h2_t); return __builtin_bit_cast(unsigned, b); }
; DI float sigmoidf_(float x) { return 1.0f / (1.0f + __expf(-x)); }
; DI void phase_proj(const Params& P, int l, char* smem) {
;     ...
;       for (int mt = 0; mt < 4; ++mt) {
;         const int row = row0 + mt * 16 + lr;
; #pragma unroll
;         for (int nt = 0; nt < 4; ++nt) {
;           f32x4 v = acc[mt][nt] * sc;
;           if (sig) { v[0] = sigmoidf_(v[0]); v[1] = sigmoidf_(v[1]); v[2] = sigmoidf_(v[2]); v[3] = sigmoidf_(v[3]); }
;           *(uint2*)(Pb + (size_t)row * PW + col0 + nt * 16 + 4 * g) = make_uint2(pack2(v[0], v[1]), pack2(v[2], v[3]));
;         }
;       }
.LBB0_682:
	s_or_b64 exec, exec, s[4:5]
	v_cvt_pk_f16_f32 v14, v14, v15
	v_cvt_pk_f16_f32 v15, v10, v11
	v_pk_mul_f32 v[6:7], v[8:9], v[6:7]
	v_pk_mul_f32 v[8:9], v[72:73], v[4:5]
	v_mov_b32_e32 v226, v14
	v_mov_b32_e32 v227, v15
	v_and_b32_e32 v232, 16, v148
	v_lshrrev_b32_e32 v233, 1, v232
	v_add_u32_e32 v232, v232, v233
	v_and_b32_e32 v233, 8, v148
	v_mul_u32_u24_e32 v233, 0x32f8, v233
	v_sub_u32_e32 v232, v232, v233
	v_ashrrev_i32_e32 v233, 31, v232
	v_lshl_add_u64 v[232:233], v[232:233], 0, v[12:13]
	v_mov_b32_e32 v236, 0x19800
	v_mov_b32_e32 v237, 0
	v_lshl_add_u64 v[234:235], v[236:237], 0, v[232:233]
	v_permlane16_swap_b32_e32 v224, v226
	v_permlane16_swap_b32_e32 v225, v227
	s_nop 1
	v_mov_b32_dpp v228, v220 row_ror:8 row_mask:0xf bank_mask:0x3
	v_mov_b32_dpp v229, v221 row_ror:8 row_mask:0xf bank_mask:0x3
	v_mov_b32_dpp v230, v222 row_ror:8 row_mask:0xf bank_mask:0x3
	v_mov_b32_dpp v231, v223 row_ror:8 row_mask:0xf bank_mask:0x3
	v_mov_b32_dpp v220, v224 row_ror:8 row_mask:0xf bank_mask:0xc
	v_mov_b32_dpp v221, v225 row_ror:8 row_mask:0xf bank_mask:0xc
	v_mov_b32_dpp v222, v226 row_ror:8 row_mask:0xf bank_mask:0xc
	v_mov_b32_dpp v223, v227 row_ror:8 row_mask:0xf bank_mask:0xc
	v_mov_b32_dpp v224, v228 quad_perm:[0,1,2,3] row_mask:0xf bank_mask:0x3
	v_mov_b32_dpp v225, v229 quad_perm:[0,1,2,3] row_mask:0xf bank_mask:0x3
	v_mov_b32_dpp v226, v230 quad_perm:[0,1,2,3] row_mask:0xf bank_mask:0x3
	v_mov_b32_dpp v227, v231 quad_perm:[0,1,2,3] row_mask:0xf bank_mask:0x3
	global_store_dwordx4 v[232:233], v[220:223], off
	global_store_dwordx4 v[234:235], v[224:227], off
	s_and_saveexec_b64 s[4:5], s[20:21]
	s_cbranch_execz .LBB0_684
	v_mul_f32_e32 v6, 0xbfb8aa3b, v6
	v_mul_f32_e32 v7, 0xbfb8aa3b, v7
	v_exp_f32_e32 v6, v6
	v_exp_f32_e32 v7, v7
	v_mul_f32_e32 v4, 0xbfb8aa3b, v8
	v_mul_f32_e32 v5, 0xbfb8aa3b, v9
	v_exp_f32_e32 v4, v4
	v_pk_add_f32 v[6:7], v[6:7], 1.0 op_sel_hi:[1,0]
	v_exp_f32_e32 v5, v5
	v_div_scale_f32 v8, s[22:23], v7, v7, 1.0
	v_rcp_f32_e32 v9, v8
	v_pk_add_f32 v[4:5], v[4:5], 1.0 op_sel_hi:[1,0]
	v_fma_f32 v10, -v8, v9, 1.0
	v_fmac_f32_e32 v9, v10, v9
	v_div_scale_f32 v10, vcc, 1.0, v7, 1.0
	v_mul_f32_e32 v11, v10, v9
	v_fma_f32 v12, -v8, v11, v10
	v_fmac_f32_e32 v11, v12, v9
	v_fma_f32 v8, -v8, v11, v10
	v_div_fmas_f32 v8, v8, v9, v11
	v_div_fixup_f32 v7, v8, v7, 1.0
	v_div_scale_f32 v8, s[22:23], v6, v6, 1.0
	v_rcp_f32_e32 v9, v8
	s_nop 0
	v_fma_f32 v10, -v8, v9, 1.0
	v_fmac_f32_e32 v9, v10, v9
	v_div_scale_f32 v10, vcc, 1.0, v6, 1.0
	v_mul_f32_e32 v11, v10, v9
	v_fma_f32 v12, -v8, v11, v10
	v_fmac_f32_e32 v11, v12, v9
	v_fma_f32 v8, -v8, v11, v10
	v_div_fmas_f32 v8, v8, v9, v11
	v_div_fixup_f32 v6, v8, v6, 1.0
	v_div_scale_f32 v8, s[22:23], v5, v5, 1.0
	v_rcp_f32_e32 v9, v8
	s_nop 0
	v_fma_f32 v10, -v8, v9, 1.0
	v_fmac_f32_e32 v9, v10, v9
	v_div_scale_f32 v10, vcc, 1.0, v5, 1.0
	v_mul_f32_e32 v11, v10, v9
	v_fma_f32 v12, -v8, v11, v10
	v_fmac_f32_e32 v11, v12, v9
	v_fma_f32 v8, -v8, v11, v10
	v_div_fmas_f32 v8, v8, v9, v11
	v_div_fixup_f32 v9, v8, v5, 1.0
	v_div_scale_f32 v5, s[22:23], v4, v4, 1.0
	v_rcp_f32_e32 v8, v5
	s_nop 0
	v_fma_f32 v10, -v5, v8, 1.0
	v_fmac_f32_e32 v8, v10, v8
	v_div_scale_f32 v10, vcc, 1.0, v4, 1.0
	v_mul_f32_e32 v11, v10, v8
	v_fma_f32 v12, -v5, v11, v10
	v_fmac_f32_e32 v11, v12, v8
	v_fma_f32 v5, -v5, v11, v10
	v_div_fmas_f32 v5, v5, v8, v11
	v_div_fixup_f32 v8, v5, v4, 1.0
.LBB0_684:
	s_or_b64 exec, exec, s[4:5]
	v_cvt_pk_f16_f32 v8, v8, v9
	v_cvt_pk_f16_f32 v9, v6, v7
	v_mov_b32_e32 v6, v72
	v_mov_b32_e32 v7, v72
	v_mad_i64_i32 v[4:5], s[4:5], v64, s0, v[28:29]
	v_pk_mul_f32 v[2:3], v[6:7], v[2:3]
	v_pk_mul_f32 v[0:1], v[72:73], v[0:1]
	v_mov_b32_e32 v220, v8
	v_mov_b32_e32 v221, v9
	s_and_saveexec_b64 s[4:5], s[20:21]
	s_cbranch_execz .LBB0_686
	v_mul_f32_e32 v2, 0xbfb8aa3b, v2
	v_mul_f32_e32 v3, 0xbfb8aa3b, v3
	v_exp_f32_e32 v2, v2
	v_exp_f32_e32 v3, v3
	v_mul_f32_e32 v0, 0xbfb8aa3b, v0
	v_mul_f32_e32 v1, 0xbfb8aa3b, v1
	v_exp_f32_e32 v0, v0
	v_pk_add_f32 v[2:3], v[2:3], 1.0 op_sel_hi:[1,0]
	v_exp_f32_e32 v1, v1
	v_div_scale_f32 v8, s[22:23], v3, v3, 1.0
	v_rcp_f32_e32 v9, v8
	v_pk_add_f32 v[0:1], v[0:1], 1.0 op_sel_hi:[1,0]
	v_fma_f32 v10, -v8, v9, 1.0
	v_fmac_f32_e32 v9, v10, v9
	v_div_scale_f32 v10, vcc, 1.0, v3, 1.0
	v_mul_f32_e32 v11, v10, v9
	v_fma_f32 v12, -v8, v11, v10
	v_fmac_f32_e32 v11, v12, v9
	v_fma_f32 v8, -v8, v11, v10
	v_div_fmas_f32 v8, v8, v9, v11
	v_div_fixup_f32 v3, v8, v3, 1.0
	v_div_scale_f32 v8, s[22:23], v2, v2, 1.0
	v_rcp_f32_e32 v9, v8
	s_nop 0
	v_fma_f32 v10, -v8, v9, 1.0
	v_fmac_f32_e32 v9, v10, v9
	v_div_scale_f32 v10, vcc, 1.0, v2, 1.0
	v_mul_f32_e32 v11, v10, v9
	v_fma_f32 v12, -v8, v11, v10
	v_fmac_f32_e32 v11, v12, v9
	v_fma_f32 v8, -v8, v11, v10
	v_div_fmas_f32 v8, v8, v9, v11
	v_div_fixup_f32 v2, v8, v2, 1.0
	v_div_scale_f32 v8, s[22:23], v1, v1, 1.0
	v_rcp_f32_e32 v9, v8
	s_nop 0
	v_fma_f32 v10, -v8, v9, 1.0
	v_fmac_f32_e32 v9, v10, v9
	v_div_scale_f32 v10, vcc, 1.0, v1, 1.0
	v_mul_f32_e32 v11, v10, v9
	v_fma_f32 v12, -v8, v11, v10
	v_fmac_f32_e32 v11, v12, v9
	v_fma_f32 v8, -v8, v11, v10
	v_div_fmas_f32 v8, v8, v9, v11
	v_div_fixup_f32 v1, v8, v1, 1.0
	v_div_scale_f32 v8, s[22:23], v0, v0, 1.0
	v_rcp_f32_e32 v9, v8
	s_nop 0
	v_fma_f32 v10, -v8, v9, 1.0
	v_fmac_f32_e32 v9, v10, v9
	v_div_scale_f32 v10, vcc, 1.0, v0, 1.0
	v_mul_f32_e32 v11, v10, v9
	v_fma_f32 v12, -v8, v11, v10
	v_fmac_f32_e32 v11, v12, v9
	v_fma_f32 v8, -v8, v11, v10
	v_div_fmas_f32 v8, v8, v9, v11
	v_div_fixup_f32 v0, v8, v0, 1.0
; DI unsigned pack2(float lo, float hi) { f2_t v = {lo, hi}; h2_t b = __builtin_convertvector(v, h2_t); return __builtin_bit_cast(unsigned, b); }
; DI float sigmoidf_(float x) { return 1.0f / (1.0f + __expf(-x)); }
; DI void phase_proj(const Params& P, int l, char* smem) {
;     ...
;       for (int mt = 0; mt < 4; ++mt) {
;         const int row = row0 + mt * 16 + lr;
; #pragma unroll
;         for (int nt = 0; nt < 4; ++nt) {
;           f32x4 v = acc[mt][nt] * sc;
;           if (sig) { v[0] = sigmoidf_(v[0]); v[1] = sigmoidf_(v[1]); v[2] = sigmoidf_(v[2]); v[3] = sigmoidf_(v[3]); }
;           *(uint2*)(Pb + (size_t)row * PW + col0 + nt * 16 + 4 * g) = make_uint2(pack2(v[0], v[1]), pack2(v[2], v[3]));
;         }
;       }
.LBB0_686:
	s_or_b64 exec, exec, s[4:5]
	v_cvt_pk_f16_f32 v0, v0, v1
	v_cvt_pk_f16_f32 v1, v2, v3
	v_mov_b32_e32 v222, v0
	v_mov_b32_e32 v223, v1
	s_nop 1
	v_permlane16_swap_b32_e32 v220, v222
	v_permlane16_swap_b32_e32 v221, v223
	v_pk_mul_f32 v[0:1], v[6:7], v[76:77]
	v_pk_mul_f32 v[2:3], v[72:73], v[74:75]
	s_and_saveexec_b64 s[4:5], s[20:21]
	s_cbranch_execz .LBB0_688
	v_mul_f32_e32 v0, 0xbfb8aa3b, v0
	v_mul_f32_e32 v1, 0xbfb8aa3b, v1
	v_exp_f32_e32 v0, v0
	v_exp_f32_e32 v1, v1
	v_mul_f32_e32 v2, 0xbfb8aa3b, v2
	v_mul_f32_e32 v3, 0xbfb8aa3b, v3
	v_exp_f32_e32 v2, v2
	v_pk_add_f32 v[0:1], v[0:1], 1.0 op_sel_hi:[1,0]
	v_exp_f32_e32 v3, v3
	v_div_scale_f32 v6, s[22:23], v1, v1, 1.0
	v_rcp_f32_e32 v7, v6
	v_pk_add_f32 v[2:3], v[2:3], 1.0 op_sel_hi:[1,0]
	v_fma_f32 v8, -v6, v7, 1.0
	v_fmac_f32_e32 v7, v8, v7
	v_div_scale_f32 v8, vcc, 1.0, v1, 1.0
	v_mul_f32_e32 v9, v8, v7
	v_fma_f32 v10, -v6, v9, v8
	v_fmac_f32_e32 v9, v10, v7
	v_fma_f32 v6, -v6, v9, v8
	v_div_fmas_f32 v6, v6, v7, v9
	v_div_fixup_f32 v1, v6, v1, 1.0
	v_div_scale_f32 v6, s[22:23], v0, v0, 1.0
	v_rcp_f32_e32 v7, v6
	s_nop 0
	v_fma_f32 v8, -v6, v7, 1.0
	v_fmac_f32_e32 v7, v8, v7
	v_div_scale_f32 v8, vcc, 1.0, v0, 1.0
	v_mul_f32_e32 v9, v8, v7
	v_fma_f32 v10, -v6, v9, v8
	v_fmac_f32_e32 v9, v10, v7
	v_fma_f32 v6, -v6, v9, v8
	v_div_fmas_f32 v6, v6, v7, v9
	v_div_fixup_f32 v0, v6, v0, 1.0
	v_div_scale_f32 v6, s[22:23], v3, v3, 1.0
	v_rcp_f32_e32 v7, v6
	s_nop 0
	v_fma_f32 v8, -v6, v7, 1.0
	v_fmac_f32_e32 v7, v8, v7
	v_div_scale_f32 v8, vcc, 1.0, v3, 1.0
	v_mul_f32_e32 v9, v8, v7
	v_fma_f32 v10, -v6, v9, v8
	v_fmac_f32_e32 v9, v10, v7
	v_fma_f32 v6, -v6, v9, v8
	v_div_fmas_f32 v6, v6, v7, v9
	v_div_fixup_f32 v3, v6, v3, 1.0
	v_div_scale_f32 v6, s[22:23], v2, v2, 1.0
	v_rcp_f32_e32 v7, v6
	s_nop 0
	v_fma_f32 v8, -v6, v7, 1.0
	v_fmac_f32_e32 v7, v8, v7
	v_div_scale_f32 v8, vcc, 1.0, v2, 1.0
	v_mul_f32_e32 v9, v8, v7
	v_fma_f32 v10, -v6, v9, v8
	v_fmac_f32_e32 v9, v10, v7
	v_fma_f32 v6, -v6, v9, v8
	v_div_fmas_f32 v6, v6, v7, v9
	v_div_fixup_f32 v2, v6, v2, 1.0
.LBB0_688:
	s_or_b64 exec, exec, s[4:5]
	v_cvt_pk_f16_f32 v2, v2, v3
	v_cvt_pk_f16_f32 v3, v0, v1
	v_mov_b32_e32 v0, v72
	v_mov_b32_e32 v1, v72
	v_mov_b32_e32 v224, v2
	v_mov_b32_e32 v225, v3
	v_pk_mul_f32 v[0:1], v[0:1], v[62:63]
	v_pk_mul_f32 v[2:3], v[72:73], v[60:61]
	s_and_saveexec_b64 s[4:5], s[20:21]
	s_cbranch_execz .LBB0_690
	v_mul_f32_e32 v0, 0xbfb8aa3b, v0
	v_mul_f32_e32 v1, 0xbfb8aa3b, v1
	v_exp_f32_e32 v0, v0
	v_exp_f32_e32 v1, v1
	v_mul_f32_e32 v2, 0xbfb8aa3b, v2
	v_mul_f32_e32 v3, 0xbfb8aa3b, v3
	v_exp_f32_e32 v2, v2
	v_pk_add_f32 v[0:1], v[0:1], 1.0 op_sel_hi:[1,0]
	v_exp_f32_e32 v3, v3
	v_div_scale_f32 v6, s[20:21], v1, v1, 1.0
	v_rcp_f32_e32 v7, v6
	v_pk_add_f32 v[2:3], v[2:3], 1.0 op_sel_hi:[1,0]
	v_fma_f32 v8, -v6, v7, 1.0
	v_fmac_f32_e32 v7, v8, v7
	v_div_scale_f32 v8, vcc, 1.0, v1, 1.0
	v_mul_f32_e32 v9, v8, v7
	v_fma_f32 v10, -v6, v9, v8
	v_fmac_f32_e32 v9, v10, v7
	v_fma_f32 v6, -v6, v9, v8
	v_div_fmas_f32 v6, v6, v7, v9
	v_div_fixup_f32 v1, v6, v1, 1.0
	v_div_scale_f32 v6, s[20:21], v0, v0, 1.0
	v_rcp_f32_e32 v7, v6
	s_nop 0
	v_fma_f32 v8, -v6, v7, 1.0
	v_fmac_f32_e32 v7, v8, v7
	v_div_scale_f32 v8, vcc, 1.0, v0, 1.0
	v_mul_f32_e32 v9, v8, v7
	v_fma_f32 v10, -v6, v9, v8
	v_fmac_f32_e32 v9, v10, v7
	v_fma_f32 v6, -v6, v9, v8
	v_div_fmas_f32 v6, v6, v7, v9
	v_div_fixup_f32 v0, v6, v0, 1.0
	v_div_scale_f32 v6, s[20:21], v3, v3, 1.0
	v_rcp_f32_e32 v7, v6
	s_nop 0
	v_fma_f32 v8, -v6, v7, 1.0
	v_fmac_f32_e32 v7, v8, v7
	v_div_scale_f32 v8, vcc, 1.0, v3, 1.0
	v_mul_f32_e32 v9, v8, v7
	v_fma_f32 v10, -v6, v9, v8
	v_fmac_f32_e32 v9, v10, v7
	v_fma_f32 v6, -v6, v9, v8
	v_div_fmas_f32 v6, v6, v7, v9
	v_div_fixup_f32 v3, v6, v3, 1.0
	v_div_scale_f32 v6, s[20:21], v2, v2, 1.0
	v_rcp_f32_e32 v7, v6
	s_nop 0
	v_fma_f32 v8, -v6, v7, 1.0
	v_fmac_f32_e32 v7, v8, v7
	v_div_scale_f32 v8, vcc, 1.0, v2, 1.0
	v_mul_f32_e32 v9, v8, v7
	v_fma_f32 v10, -v6, v9, v8
	v_fmac_f32_e32 v9, v10, v7
	v_fma_f32 v6, -v6, v9, v8
	v_div_fmas_f32 v6, v6, v7, v9
	v_div_fixup_f32 v2, v6, v2, 1.0
.LBB0_690:
	s_or_b64 exec, exec, s[4:5]
	v_cvt_pk_f16_f32 v2, v2, v3
	v_cvt_pk_f16_f32 v3, v0, v1
	s_mov_b64 s[4:5], 0
	v_mov_b32_e32 v226, v2
	v_mov_b32_e32 v227, v3
	v_and_b32_e32 v232, 16, v148
	v_lshrrev_b32_e32 v233, 1, v232
	v_add_u32_e32 v232, v232, v233
	v_and_b32_e32 v233, 8, v148
	v_mul_u32_u24_e32 v233, 0x32f8, v233
	v_sub_u32_e32 v232, v232, v233
	v_ashrrev_i32_e32 v233, 31, v232
	v_lshl_add_u64 v[232:233], v[232:233], 0, v[4:5]
	v_mov_b32_e32 v236, 0x19800
	v_mov_b32_e32 v237, 0
	v_lshl_add_u64 v[234:235], v[236:237], 0, v[232:233]
	v_permlane16_swap_b32_e32 v224, v226
	v_permlane16_swap_b32_e32 v225, v227
	s_nop 1
	v_mov_b32_dpp v228, v220 row_ror:8 row_mask:0xf bank_mask:0x3
	v_mov_b32_dpp v229, v221 row_ror:8 row_mask:0xf bank_mask:0x3
	v_mov_b32_dpp v230, v222 row_ror:8 row_mask:0xf bank_mask:0x3
	v_mov_b32_dpp v231, v223 row_ror:8 row_mask:0xf bank_mask:0x3
	v_mov_b32_dpp v220, v224 row_ror:8 row_mask:0xf bank_mask:0xc
	v_mov_b32_dpp v221, v225 row_ror:8 row_mask:0xf bank_mask:0xc
	v_mov_b32_dpp v222, v226 row_ror:8 row_mask:0xf bank_mask:0xc
	v_mov_b32_dpp v223, v227 row_ror:8 row_mask:0xf bank_mask:0xc
	v_mov_b32_dpp v224, v228 quad_perm:[0,1,2,3] row_mask:0xf bank_mask:0x3
	v_mov_b32_dpp v225, v229 quad_perm:[0,1,2,3] row_mask:0xf bank_mask:0x3
	v_mov_b32_dpp v226, v230 quad_perm:[0,1,2,3] row_mask:0xf bank_mask:0x3
	v_mov_b32_dpp v227, v231 quad_perm:[0,1,2,3] row_mask:0xf bank_mask:0x3
	global_store_dwordx4 v[232:233], v[220:223], off
	global_store_dwordx4 v[234:235], v[224:227], off
